# cross attention: K tile fetched once per workgroup into LDS (each wave 1/8, coalesced) and MFMA fragments read from LDS, on top of the (batch, head)-per-workgroup item remap
# speedup vs baseline: 1.0081x; 1.0081x over previous
; __device__ __forceinline__ void xattn_mfma_item(const bf16* qx, const bf16* kv, bf16* ox, LAS unsigned char* wl, int item, int lane) {
;     const int head = item & 3, qblk = item >> 2;
;     const int r = lane & 31, hi = lane >> 5;
;     const int token = qblk * 32 + r, b = (qblk * 32) / S;
;     s16x8 Qf[8];
;     { const char* qb_ = (const char*)qx; const unsigned qo = (unsigned)(token * DX + head * 128 + 8 * hi) * 2u;
; #pragma unroll
;       for (int d0 = 0; d0 < 8; ++d0) Qf[d0] = *(const s16x8*)(qb_ + qo + 32 * d0); }
;     f32x16 O[4];
; #pragma unroll
;     for (int k = 0; k < 4; ++k)
; #pragma unroll
;         for (int i = 0; i < 16; ++i) O[k][i] = 0.f;
;     float mrun = -1e30f, lsum = 0.f;
;     const int trbase = (4 * hi + ((lane >> 2) & 3)) * PV128 + (16 * ((lane >> 4) & 1) + 4 * (lane & 3)) * 2;
;     const char* kvc = (const char*)(kv + (size_t)b * MEML * 1024);
;     const unsigned kfo = (unsigned)(r * 1024 + head * 128 + 8 * hi) * 2u;
;     const unsigned vlo = (unsigned)((lane >> 4) * 1024 + 512 + head * 128 + 8 * (lane & 15)) * 2u;
;     s16x8 Kn[8]; v4u vn[8];
; #pragma unroll
;     for (int d0 = 0; d0 < 8; ++d0) Kn[d0] = *(const s16x8*)(kvc + kfo + 32 * d0);
; #pragma unroll
;     for (int i = 0; i < 8; ++i) vn[i] = *(const v4u*)(kvc + vlo + (size_t)(4 * i) * 2048);
.LBB0_590:
	s_and_b32 s2, s14, 0x180
	s_lshl_b32 s3, s10, 7
	v_add_lshl_u32 v2, v222, s2, 1
	v_add_lshl_u32 v4, v221, s2, 1
	s_lshl_b32 s2, s10, 3
	s_and_b32 s17, s3, 0x180
	s_bfe_i32 s3, s10, 0x1001c
	s_andn2_b32 s2, s2, 31
	s_lshr_b32 s3, s3, 21
	v_or_b32_e32 v6, s2, v203
	s_add_i32 s2, s2, s3
	v_lshl_or_b32 v225, v6, 9, s17
	s_ashr_i32 s2, s2, 11
	v_or_b32_e32 v6, v225, v219
	v_readlane_b32 s18, v253, 47
	s_ashr_i32 s3, s2, 31
	v_lshlrev_b32_e32 v6, 1, v6
	v_readlane_b32 s19, v253, 48
	s_lshl_b64 s[2:3], s[2:3], 19
	s_nop 3
	global_load_dwordx4 v[130:133], v6, s[18:19]
	global_load_dwordx4 v[126:129], v6, s[18:19] offset:32
	global_load_dwordx4 v[122:125], v6, s[18:19] offset:64
	global_load_dwordx4 v[118:121], v6, s[18:19] offset:96
	global_load_dwordx4 v[114:117], v6, s[18:19] offset:128
	global_load_dwordx4 v[110:113], v6, s[18:19] offset:160
	global_load_dwordx4 v[102:105], v6, s[18:19] offset:192
	global_load_dwordx4 v[98:101], v6, s[18:19] offset:224
	s_add_u32 s18, s1, s2
	v_or_b32_e32 v6, s17, v221
	s_addc_u32 s19, s11, s3
	v_lshlrev_b32_e32 v7, 1, v6
	v_or_b32_e32 v6, s17, v222
	v_lshlrev_b32_e32 v6, 1, v6
	v_readlane_b32 s21, v253, 51
	v_lshrrev_b32_e32 v234, 4, v202
	v_and_b32_e32 v235, 15, v202
	v_lshrrev_b32_e32 v238, 5, v202
	v_lshl_add_u32 v234, s21, 2, v234
	v_lshlrev_b32_e32 v235, 4, v235
	v_lshl_add_u32 v236, v234, 11, v235
	v_lshl_add_u32 v236, s17, 1, v236
	v_mov_b32_e32 v237, 0
	v_lshl_add_u64 v[232:233], s[18:19], 0, v[236:237]
	global_load_dwordx4 v[228:231], v[232:233], off
	v_mul_u32_u24_e32 v234, 0x110, v234
	v_add_u32_e32 v234, v234, v235
	v_add_u32_e32 v234, 0x20000, v234
	v_mul_u32_u24_e32 v235, 0x110, v203
	v_lshl_add_u32 v235, v238, 4, v235
	v_add_u32_e32 v235, 0x20000, v235
	v_mov_b32_e32 v7, v3
	v_lshl_add_u64 v[8:9], s[18:19], 0, v[6:7]
	global_load_dwordx4 v[162:165], v6, s[18:19] offset:1024
	v_add_co_u32_e32 v6, vcc, s83, v8
	s_movk_i32 s17, 0x6000
	s_nop 0
	v_addc_co_u32_e32 v7, vcc, 0, v9, vcc
	global_load_dwordx4 v[166:169], v[6:7], off offset:1024
	v_add_co_u32_e32 v6, vcc, s88, v8
	s_add_u32 s18, s12, s2
	s_nop 0
	v_addc_co_u32_e32 v7, vcc, 0, v9, vcc
	global_load_dwordx4 v[170:173], v[6:7], off offset:1024
	v_add_co_u32_e32 v6, vcc, s17, v8
	s_mov_b32 s17, 0x8000
	s_nop 0
	v_addc_co_u32_e32 v7, vcc, 0, v9, vcc
	global_load_dwordx4 v[174:177], v[6:7], off offset:1024
	v_add_co_u32_e32 v6, vcc, s17, v8
	s_mov_b32 s17, 0xa000
	s_nop 0
	v_addc_co_u32_e32 v7, vcc, 0, v9, vcc
	global_load_dwordx4 v[178:181], v[6:7], off offset:1024
	v_add_co_u32_e32 v6, vcc, s17, v8
	s_mov_b32 s17, 0xc000
	s_nop 0
	v_addc_co_u32_e32 v7, vcc, 0, v9, vcc
	global_load_dwordx4 v[182:185], v[6:7], off offset:1024
	v_add_co_u32_e32 v6, vcc, s17, v8
	s_mov_b32 s17, 0xe000
	s_nop 0
	v_addc_co_u32_e32 v7, vcc, 0, v9, vcc
	global_load_dwordx4 v[186:189], v[6:7], off offset:1024
	v_add_co_u32_e32 v6, vcc, s17, v8
	s_addc_u32 s19, s13, s3
	s_nop 0
	v_addc_co_u32_e32 v7, vcc, 0, v9, vcc
	global_load_dwordx4 v[190:193], v[6:7], off offset:1024
	s_add_u32 s2, s15, s2
	v_mov_b32_e32 v5, v3
	s_addc_u32 s3, s16, s3
	v_mov_b32_e32 v16, v3
	v_mov_b32_e32 v17, v3
	v_lshl_add_u64 v[204:205], s[18:19], 0, v[2:3]
	v_lshl_add_u64 v[206:207], s[2:3], 0, v[4:5]
	v_mov_b32_e32 v2, v3
	v_mov_b32_e32 v4, v3
	v_mov_b32_e32 v6, v3
	v_mov_b32_e32 v7, v3
	v_mov_b32_e32 v8, v3
	v_mov_b32_e32 v9, v3
	v_mov_b32_e32 v10, v3
	v_mov_b32_e32 v11, v3
	v_mov_b32_e32 v12, v3
	v_mov_b32_e32 v13, v3
	v_mov_b32_e32 v14, v3
	v_mov_b32_e32 v15, v3
	v_mov_b64_e32 v[32:33], v[16:17]
	v_mov_b64_e32 v[48:49], v[16:17]
	v_mov_b64_e32 v[64:65], v[16:17]
	v_mov_b64_e32 v[80:81], v[16:17]
	v_mov_b32_e32 v226, 0
	v_mov_b32_e32 v227, 0xf149f2ca
	s_mov_b64 s[2:3], 0
	v_mov_b64_e32 v[30:31], v[14:15]
	v_mov_b64_e32 v[28:29], v[12:13]
	v_mov_b64_e32 v[26:27], v[10:11]
	v_mov_b64_e32 v[24:25], v[8:9]
	v_mov_b64_e32 v[22:23], v[6:7]
	v_mov_b64_e32 v[20:21], v[4:5]
	v_mov_b64_e32 v[18:19], v[2:3]
	v_mov_b64_e32 v[46:47], v[14:15]
	v_mov_b64_e32 v[44:45], v[12:13]
	v_mov_b64_e32 v[42:43], v[10:11]
	v_mov_b64_e32 v[40:41], v[8:9]
	v_mov_b64_e32 v[38:39], v[6:7]
	v_mov_b64_e32 v[36:37], v[4:5]
	v_mov_b64_e32 v[34:35], v[2:3]
	v_mov_b64_e32 v[62:63], v[14:15]
	v_mov_b64_e32 v[60:61], v[12:13]
	v_mov_b64_e32 v[58:59], v[10:11]
	v_mov_b64_e32 v[56:57], v[8:9]
	v_mov_b64_e32 v[54:55], v[6:7]
	v_mov_b64_e32 v[52:53], v[4:5]
	v_mov_b64_e32 v[50:51], v[2:3]
	v_mov_b64_e32 v[78:79], v[14:15]
	v_mov_b64_e32 v[76:77], v[12:13]
	v_mov_b64_e32 v[74:75], v[10:11]
	v_mov_b64_e32 v[72:73], v[8:9]
	v_mov_b64_e32 v[70:71], v[6:7]
	v_mov_b64_e32 v[68:69], v[4:5]
	v_mov_b64_e32 v[66:67], v[2:3]
	s_waitcnt vmcnt(8)
	ds_write_b128 v234, v[228:231]
	s_waitcnt lgkmcnt(0)
	s_barrier
	ds_read_b128 v[158:161], v235
	ds_read_b128 v[154:157], v235 offset:32
	ds_read_b128 v[150:153], v235 offset:64
	ds_read_b128 v[146:149], v235 offset:96
	ds_read_b128 v[142:145], v235 offset:128
	ds_read_b128 v[138:141], v235 offset:160
	ds_read_b128 v[134:137], v235 offset:192
	ds_read_b128 v[106:109], v235 offset:224
	v_add_co_u32_e32 v232, vcc, 0x10000, v232
	s_nop 1
	v_addc_co_u32_e32 v233, vcc, 0, v233, vcc
	global_load_dwordx4 v[228:231], v[232:233], off
	s_branch .LBB0_592

; #define LAS __attribute__((address_space(3)))
; #define MFMA32(a, b, c) __builtin_amdgcn_mfma_f32_32x32x16_bf16(a, b, c, 0, 0, 0)
; __device__ __forceinline__ float xh_max(float x) { auto rr = __builtin_amdgcn_permlane32_swap(__float_as_uint(x), __float_as_uint(x), false, false); return fmaxf(__uint_as_float(rr[0]), __uint_as_float(rr[1])); }
; __device__ __forceinline__ void xattn_mfma_item(const bf16* qx, const bf16* kv, bf16* ox, LAS unsigned char* wl, int item, int lane) {
;     ...
;     for (int jt = 0; jt < 8; ++jt) {
;         f32x16 Sx;
; #pragma unroll
;         for (int i = 0; i < 16; ++i) Sx[i] = 0.f;
; #pragma unroll
;         for (int d0 = 0; d0 < 8; ++d0) Sx = MFMA32(Kn[d0], Qf[d0], Sx);
;         { LAS unsigned char* dst = wl + (lane >> 4) * PV128 + 16 * (lane & 15);
; #pragma unroll
;           for (int i = 0; i < 8; ++i) *(LAS v4u*)(dst + 4 * i * PV128) = vn[i]; }
;         if (jt < 7) { const char* tb = kvc + (size_t)((jt + 1) * 32) * 2048;
; #pragma unroll
;             for (int d0 = 0; d0 < 8; ++d0) Kn[d0] = *(const s16x8*)(tb + kfo + 32 * d0);
; #pragma unroll
;             for (int i = 0; i < 8; ++i) vn[i] = *(const v4u*)(tb + vlo + (size_t)(4 * i) * 2048); }
;         float P[16]; float tmax = -1e30f;
; #pragma unroll
;         for (int i = 0; i < 16; ++i) { P[i] = Sx[i] * SCX; tmax = fmaxf(tmax, P[i]); }
;         tmax = xh_max(tmax);
;         if (__any(tmax > mrun)) { const float mnew = fmaxf(mrun, tmax), alpha = __builtin_amdgcn_exp2f(mrun - mnew); lsum *= alpha; mrun = mnew;
.LBB0_592:
	s_waitcnt lgkmcnt(0)
	v_mfma_f32_32x32x16_bf16 v[82:97], v[158:161], v[130:133], 0
	s_waitcnt vmcnt(7)
	ds_write_b128 v223, v[162:165]
	s_waitcnt vmcnt(6)
	ds_write_b128 v223, v[166:169] offset:1088
	s_waitcnt vmcnt(5)
	ds_write_b128 v223, v[170:173] offset:2176
	s_waitcnt vmcnt(4)
	ds_write_b128 v223, v[174:177] offset:3264
	s_waitcnt vmcnt(3)
	ds_write_b128 v223, v[178:181] offset:4352
	s_waitcnt vmcnt(2)
	ds_write_b128 v223, v[182:185] offset:5440
	s_waitcnt vmcnt(1)
	ds_write_b128 v223, v[186:189] offset:6528
	s_waitcnt vmcnt(0)
	ds_write_b128 v223, v[190:193] offset:7616
	s_mov_b32 s17, 0xf010000
	v_mfma_f32_32x32x16_bf16 v[82:97], v[154:157], v[126:129], v[82:97]
	v_mfma_f32_32x32x16_bf16 v[82:97], v[150:153], v[122:125], v[82:97]
	v_mfma_f32_32x32x16_bf16 v[82:97], v[146:149], v[118:121], v[82:97]
	v_mfma_f32_32x32x16_bf16 v[82:97], v[142:145], v[114:117], v[82:97]
	v_mfma_f32_32x32x16_bf16 v[82:97], v[138:141], v[110:113], v[82:97]
	v_mfma_f32_32x32x16_bf16 v[82:97], v[134:137], v[102:105], v[82:97]
	v_mfma_f32_32x32x16_bf16 v[82:97], v[106:109], v[98:101], v[82:97]
	s_barrier
	ds_write_b128 v234, v[228:231]
	s_waitcnt lgkmcnt(0)
	s_barrier
	ds_read_b128 v[158:161], v235
	ds_read_b128 v[154:157], v235 offset:32
	ds_read_b128 v[150:153], v235 offset:64
	ds_read_b128 v[146:149], v235 offset:96
	ds_read_b128 v[142:145], v235 offset:128
	ds_read_b128 v[138:141], v235 offset:160
	ds_read_b128 v[134:137], v235 offset:192
	ds_read_b128 v[106:109], v235 offset:224
	s_cmp_gt_u32 s2, 0x50000
	s_cbranch_scc1 .Lxa_nopiece
	v_add_co_u32_e32 v232, vcc, 0x10000, v232
	s_nop 1
	v_addc_co_u32_e32 v233, vcc, 0, v233, vcc
	global_load_dwordx4 v[228:231], v[232:233], off
.Lxa_nopiece:
	v_lshl_add_u64 v[4:5], v[204:205], 0, s[2:3]
	v_add_co_u32_e32 v6, vcc, s17, v4
	s_mov_b32 s17, 0xf012000
	s_nop 0
	v_addc_co_u32_e32 v7, vcc, 0, v5, vcc
	v_add_co_u32_e32 v8, vcc, s17, v4
	s_mov_b32 s17, 0xf014000
	s_nop 0
	v_addc_co_u32_e32 v9, vcc, 0, v5, vcc
	global_load_dwordx4 v[162:165], v[6:7], off offset:1024
	global_load_dwordx4 v[166:169], v[8:9], off offset:1024
	v_add_co_u32_e32 v6, vcc, s17, v4
	s_mov_b32 s17, 0xf016000
	s_nop 0
	v_addc_co_u32_e32 v7, vcc, 0, v5, vcc
	v_add_co_u32_e32 v8, vcc, s17, v4
	s_mov_b32 s17, 0xf018000
	s_nop 0
	v_addc_co_u32_e32 v9, vcc, 0, v5, vcc
	global_load_dwordx4 v[170:173], v[6:7], off offset:1024
	global_load_dwordx4 v[174:177], v[8:9], off offset:1024
	v_add_co_u32_e32 v6, vcc, s17, v4
	s_mov_b32 s17, 0xf01a000
	s_nop 0
	v_addc_co_u32_e32 v7, vcc, 0, v5, vcc
	v_add_co_u32_e32 v8, vcc, s17, v4
	s_mov_b32 s17, 0xf01c000
	s_nop 0
	v_addc_co_u32_e32 v9, vcc, 0, v5, vcc
	global_load_dwordx4 v[178:181], v[6:7], off offset:1024
	global_load_dwordx4 v[182:185], v[8:9], off offset:1024
	v_add_co_u32_e32 v6, vcc, s17, v4
	s_mov_b32 s17, 0xf01e000
	s_nop 0
	v_addc_co_u32_e32 v7, vcc, 0, v5, vcc
	v_add_co_u32_e32 v4, vcc, s17, v4
	v_mul_f32_e32 v82, 0x3e0293ee, v82
	s_nop 0
	v_addc_co_u32_e32 v5, vcc, 0, v5, vcc
	global_load_dwordx4 v[186:189], v[6:7], off offset:1024
	global_load_dwordx4 v[190:193], v[4:5], off offset:1024
	v_mul_f32_e32 v17, 0x3e0293ee, v83
	s_mov_b32 s17, 0xf149f2ca
	v_max3_f32 v2, v82, s17, v17
	v_mul_f32_e32 v16, 0x3e0293ee, v84
	v_mul_f32_e32 v15, 0x3e0293ee, v85
	v_max3_f32 v2, v2, v16, v15
	v_mul_f32_e32 v14, 0x3e0293ee, v86
	v_mul_f32_e32 v13, 0x3e0293ee, v87
	v_max3_f32 v2, v2, v14, v13
	v_mul_f32_e32 v12, 0x3e0293ee, v88
	v_mul_f32_e32 v11, 0x3e0293ee, v89
	v_max3_f32 v2, v2, v12, v11
	v_mul_f32_e32 v10, 0x3e0293ee, v90
	v_mul_f32_e32 v9, 0x3e0293ee, v91
	v_max3_f32 v2, v2, v10, v9
	v_mul_f32_e32 v8, 0x3e0293ee, v92
	v_mul_f32_e32 v7, 0x3e0293ee, v93
	v_max3_f32 v2, v2, v8, v7
	v_mul_f32_e32 v6, 0x3e0293ee, v94
	v_mul_f32_e32 v5, 0x3e0293ee, v95
	v_max3_f32 v83, v2, v6, v5
	v_mul_f32_e32 v4, 0x3e0293ee, v96
	v_mul_f32_e32 v2, 0x3e0293ee, v97
	v_max3_f32 v83, v83, v4, v2
	v_mov_b32_e32 v84, v83
	s_nop 1
	v_permlane32_swap_b32_e32 v83, v84
	v_max_f32_e32 v84, v84, v84
	v_max_f32_e32 v83, v83, v83
	v_max_f32_e32 v83, v83, v84
	v_cmp_gt_f32_e32 vcc, v83, v227
	s_cbranch_vccz .LBB0_591
	v_max_f32_e32 v83, v83, v83
	v_max_f32_e32 v84, v227, v227
	v_max_f32_e32 v83, v84, v83
	v_sub_f32_e32 v84, v227, v83
	v_exp_f32_e32 v84, v84
	v_mov_b32_e32 v227, v83
	v_pk_mul_f32 v[80:81], v[80:81], v[84:85] op_sel_hi:[1,0]
	v_pk_mul_f32 v[78:79], v[78:79], v[84:85] op_sel_hi:[1,0]
	v_pk_mul_f32 v[76:77], v[76:77], v[84:85] op_sel_hi:[1,0]
	v_pk_mul_f32 v[74:75], v[74:75], v[84:85] op_sel_hi:[1,0]
	v_pk_mul_f32 v[72:73], v[72:73], v[84:85] op_sel_hi:[1,0]
	v_pk_mul_f32 v[70:71], v[70:71], v[84:85] op_sel_hi:[1,0]
	v_pk_mul_f32 v[68:69], v[68:69], v[84:85] op_sel_hi:[1,0]
	v_pk_mul_f32 v[66:67], v[66:67], v[84:85] op_sel_hi:[1,0]
	v_pk_mul_f32 v[64:65], v[64:65], v[84:85] op_sel_hi:[1,0]
	v_pk_mul_f32 v[62:63], v[62:63], v[84:85] op_sel_hi:[1,0]
	v_pk_mul_f32 v[60:61], v[60:61], v[84:85] op_sel_hi:[1,0]
	v_pk_mul_f32 v[58:59], v[58:59], v[84:85] op_sel_hi:[1,0]
	v_pk_mul_f32 v[56:57], v[56:57], v[84:85] op_sel_hi:[1,0]
	v_pk_mul_f32 v[54:55], v[54:55], v[84:85] op_sel_hi:[1,0]
	v_pk_mul_f32 v[52:53], v[52:53], v[84:85] op_sel_hi:[1,0]
	v_pk_mul_f32 v[50:51], v[50:51], v[84:85] op_sel_hi:[1,0]
	v_pk_mul_f32 v[48:49], v[48:49], v[84:85] op_sel_hi:[1,0]
	v_pk_mul_f32 v[46:47], v[46:47], v[84:85] op_sel_hi:[1,0]
	v_pk_mul_f32 v[44:45], v[44:45], v[84:85] op_sel_hi:[1,0]
	v_pk_mul_f32 v[42:43], v[42:43], v[84:85] op_sel_hi:[1,0]
	v_pk_mul_f32 v[40:41], v[40:41], v[84:85] op_sel_hi:[1,0]
	v_pk_mul_f32 v[38:39], v[38:39], v[84:85] op_sel_hi:[1,0]
	v_pk_mul_f32 v[36:37], v[36:37], v[84:85] op_sel_hi:[1,0]
	v_pk_mul_f32 v[34:35], v[34:35], v[84:85] op_sel_hi:[1,0]
	v_pk_mul_f32 v[32:33], v[32:33], v[84:85] op_sel_hi:[1,0]
	v_pk_mul_f32 v[30:31], v[30:31], v[84:85] op_sel_hi:[1,0]
	v_pk_mul_f32 v[28:29], v[28:29], v[84:85] op_sel_hi:[1,0]
	v_pk_mul_f32 v[26:27], v[26:27], v[84:85] op_sel_hi:[1,0]
	v_pk_mul_f32 v[24:25], v[24:25], v[84:85] op_sel_hi:[1,0]
	v_pk_mul_f32 v[22:23], v[22:23], v[84:85] op_sel_hi:[1,0]
	v_pk_mul_f32 v[20:21], v[20:21], v[84:85] op_sel_hi:[1,0]
	v_pk_mul_f32 v[18:19], v[18:19], v[84:85] op_sel_hi:[1,0]
	v_mul_f32_e32 v226, v226, v84
	s_branch .LBB0_591
; #define LAS __attribute__((address_space(3)))
; #define MFMA32(a, b, c) __builtin_amdgcn_mfma_f32_32x32x16_bf16(a, b, c, 0, 0, 0)
; __device__ __forceinline__ float xh_max(float x) { auto rr = __builtin_amdgcn_permlane32_swap(__float_as_uint(x), __float_as_uint(x), false, false); return fmaxf(__uint_as_float(rr[0]), __uint_as_float(rr[1])); }
; __device__ __forceinline__ void xattn_mfma_item(const bf16* qx, const bf16* kv, bf16* ox, LAS unsigned char* wl, int item, int lane) {
;     ...
;     for (int jt = 0; jt < 8; ++jt) {
;         f32x16 Sx;
; #pragma unroll
;         for (int i = 0; i < 16; ++i) Sx[i] = 0.f;
; #pragma unroll
;         for (int d0 = 0; d0 < 8; ++d0) Sx = MFMA32(Kn[d0], Qf[d0], Sx);
;         { LAS unsigned char* dst = wl + (lane >> 4) * PV128 + 16 * (lane & 15);
; #pragma unroll
;           for (int i = 0; i < 8; ++i) *(LAS v4u*)(dst + 4 * i * PV128) = vn[i]; }
;         if (jt < 7) { const char* tb = kvc + (size_t)((jt + 1) * 32) * 2048;
; #pragma unroll
;             for (int d0 = 0; d0 < 8; ++d0) Kn[d0] = *(const s16x8*)(tb + kfo + 32 * d0);
; #pragma unroll
;             for (int i = 0; i < 8; ++i) vn[i] = *(const v4u*)(tb + vlo + (size_t)(4 * i) * 2048); }
;         float P[16]; float tmax = -1e30f;
; #pragma unroll
;         for (int i = 0; i < 16; ++i) { P[i] = Sx[i] * SCX; tmax = fmaxf(tmax, P[i]); }
;         tmax = xh_max(tmax);
;         if (__any(tmax > mrun)) { const float mnew = fmaxf(mrun, tmax), alpha = __builtin_amdgcn_exp2f(mrun - mnew); lsum *= alpha; mrun = mnew;
; #pragma unroll
;             for (int k = 0; k < 4; ++k)
; #pragma unroll
;                 for (int i = 0; i < 16; ++i) O[k][i] *= alpha; }
.LBB0_594:
	s_waitcnt lgkmcnt(0)
	v_mfma_f32_32x32x16_bf16 v[82:97], v[158:161], v[130:133], 0
	s_mov_b32 s2, 0xf149f2ca
	s_waitcnt vmcnt(7)
	ds_write_b128 v223, v[162:165]
	s_waitcnt vmcnt(6)
	ds_write_b128 v223, v[166:169] offset:1088
	s_waitcnt vmcnt(5)
	ds_write_b128 v223, v[170:173] offset:2176
	s_waitcnt vmcnt(4)
	ds_write_b128 v223, v[174:177] offset:3264
	s_waitcnt vmcnt(3)
	ds_write_b128 v223, v[178:181] offset:4352
	s_waitcnt vmcnt(2)
	ds_write_b128 v223, v[182:185] offset:5440
	s_waitcnt vmcnt(1)
	ds_write_b128 v223, v[186:189] offset:6528
	s_waitcnt vmcnt(0)
	ds_write_b128 v223, v[190:193] offset:7616
	v_mfma_f32_32x32x16_bf16 v[82:97], v[154:157], v[126:129], v[82:97]
	v_mfma_f32_32x32x16_bf16 v[82:97], v[150:153], v[122:125], v[82:97]
	v_mfma_f32_32x32x16_bf16 v[82:97], v[146:149], v[118:121], v[82:97]
	v_mfma_f32_32x32x16_bf16 v[82:97], v[142:145], v[114:117], v[82:97]
	v_mfma_f32_32x32x16_bf16 v[82:97], v[138:141], v[110:113], v[82:97]
	v_mfma_f32_32x32x16_bf16 v[82:97], v[134:137], v[102:105], v[82:97]
	v_mfma_f32_32x32x16_bf16 v[82:97], v[106:109], v[98:101], v[82:97]
	s_nop 11
	v_mul_f32_e32 v82, 0x3e0293ee, v82
	v_mul_f32_e32 v16, 0x3e0293ee, v83
	v_max3_f32 v2, v82, s2, v16
	v_mul_f32_e32 v17, 0x3e0293ee, v84
	v_mul_f32_e32 v15, 0x3e0293ee, v85
	v_max3_f32 v2, v2, v17, v15
	v_mul_f32_e32 v14, 0x3e0293ee, v86
	v_mul_f32_e32 v13, 0x3e0293ee, v87
	v_max3_f32 v2, v2, v14, v13
	v_mul_f32_e32 v12, 0x3e0293ee, v88
	v_mul_f32_e32 v11, 0x3e0293ee, v89
	v_max3_f32 v2, v2, v12, v11
	v_mul_f32_e32 v10, 0x3e0293ee, v90
	v_mul_f32_e32 v9, 0x3e0293ee, v91
	v_max3_f32 v2, v2, v10, v9
	v_mul_f32_e32 v8, 0x3e0293ee, v92
	v_mul_f32_e32 v7, 0x3e0293ee, v93
	v_max3_f32 v2, v2, v8, v7
	v_mul_f32_e32 v6, 0x3e0293ee, v94
	v_mul_f32_e32 v5, 0x3e0293ee, v95
	v_max3_f32 v83, v2, v6, v5
	v_mul_f32_e32 v4, 0x3e0293ee, v96
	v_mul_f32_e32 v2, 0x3e0293ee, v97
	v_max3_f32 v83, v83, v4, v2
	v_mov_b32_e32 v84, v83
	s_nop 1
	v_permlane32_swap_b32_e32 v83, v84
	v_max_f32_e32 v84, v84, v84
	v_max_f32_e32 v83, v83, v83
	v_max_f32_e32 v83, v83, v84
	v_cmp_gt_f32_e32 vcc, v83, v227
	s_cbranch_vccz .LBB0_589
	v_max_f32_e32 v83, v83, v83
	v_max_f32_e32 v84, v227, v227
	v_max_f32_e32 v83, v84, v83
	v_sub_f32_e32 v84, v227, v83
	v_exp_f32_e32 v84, v84
	v_mov_b32_e32 v227, v83
	v_pk_mul_f32 v[80:81], v[80:81], v[84:85] op_sel_hi:[1,0]
	v_pk_mul_f32 v[78:79], v[78:79], v[84:85] op_sel_hi:[1,0]
	v_pk_mul_f32 v[76:77], v[76:77], v[84:85] op_sel_hi:[1,0]
	v_pk_mul_f32 v[74:75], v[74:75], v[84:85] op_sel_hi:[1,0]
	v_pk_mul_f32 v[72:73], v[72:73], v[84:85] op_sel_hi:[1,0]
	v_pk_mul_f32 v[70:71], v[70:71], v[84:85] op_sel_hi:[1,0]
	v_pk_mul_f32 v[68:69], v[68:69], v[84:85] op_sel_hi:[1,0]
	v_pk_mul_f32 v[66:67], v[66:67], v[84:85] op_sel_hi:[1,0]
	v_pk_mul_f32 v[64:65], v[64:65], v[84:85] op_sel_hi:[1,0]
	v_pk_mul_f32 v[62:63], v[62:63], v[84:85] op_sel_hi:[1,0]
	v_pk_mul_f32 v[60:61], v[60:61], v[84:85] op_sel_hi:[1,0]
	v_pk_mul_f32 v[58:59], v[58:59], v[84:85] op_sel_hi:[1,0]
	v_pk_mul_f32 v[56:57], v[56:57], v[84:85] op_sel_hi:[1,0]
	v_pk_mul_f32 v[54:55], v[54:55], v[84:85] op_sel_hi:[1,0]
	v_pk_mul_f32 v[52:53], v[52:53], v[84:85] op_sel_hi:[1,0]
	v_pk_mul_f32 v[50:51], v[50:51], v[84:85] op_sel_hi:[1,0]
	v_pk_mul_f32 v[48:49], v[48:49], v[84:85] op_sel_hi:[1,0]
	v_pk_mul_f32 v[46:47], v[46:47], v[84:85] op_sel_hi:[1,0]
	v_pk_mul_f32 v[44:45], v[44:45], v[84:85] op_sel_hi:[1,0]
	v_pk_mul_f32 v[42:43], v[42:43], v[84:85] op_sel_hi:[1,0]
	v_pk_mul_f32 v[40:41], v[40:41], v[84:85] op_sel_hi:[1,0]
	v_pk_mul_f32 v[38:39], v[38:39], v[84:85] op_sel_hi:[1,0]
	v_pk_mul_f32 v[36:37], v[36:37], v[84:85] op_sel_hi:[1,0]
	v_pk_mul_f32 v[34:35], v[34:35], v[84:85] op_sel_hi:[1,0]
	v_pk_mul_f32 v[32:33], v[32:33], v[84:85] op_sel_hi:[1,0]
	v_pk_mul_f32 v[30:31], v[30:31], v[84:85] op_sel_hi:[1,0]
	v_pk_mul_f32 v[28:29], v[28:29], v[84:85] op_sel_hi:[1,0]
	v_pk_mul_f32 v[26:27], v[26:27], v[84:85] op_sel_hi:[1,0]
	v_pk_mul_f32 v[24:25], v[24:25], v[84:85] op_sel_hi:[1,0]
	v_pk_mul_f32 v[22:23], v[22:23], v[84:85] op_sel_hi:[1,0]
	v_pk_mul_f32 v[20:21], v[20:21], v[84:85] op_sel_hi:[1,0]
	v_pk_mul_f32 v[18:19], v[18:19], v[84:85] op_sel_hi:[1,0]
	v_mul_f32_e32 v226, v226, v84
	s_branch .LBB0_589
